# baseline (speedup 1.0000x reference)
; #define PG8_STAGE(bufoff, gbase, voff) do { _Pragma("unroll") for (int _i = 0; _i < 2; ++_i) \
;         __builtin_amdgcn_global_load_lds((const unsigned*)((const char*)(gbase) + (voff)[_i]), (LAS unsigned*)(lds + (bufoff) + ldsw + _i * 8192), 16, 0, 0); } while (0)
; #define PG8_LDA(dst, b, h) do { _Pragma("unroll") for (int m = 0; m < 4; ++m) _Pragma("unroll") for (int k = 0; k < 2; ++k) dst[m][k] = *(const LAS bf16x8*)(lds + PG8_SA(b, h) + aoff + m * 2048 + k * 1024); } while (0)
; #define PG8_LDB(dst, b, h) do { _Pragma("unroll") for (int n = 0; n < 2; ++n) _Pragma("unroll") for (int k = 0; k < 2; ++k) dst[n][k] = *(const LAS bf16x8*)(lds + PG8_SB(b, h) + boff + n * 2048 + k * 1024); } while (0)
; #define PG8_MMA(ai, bj, At, Bt) do { __builtin_amdgcn_s_setprio(1); _Pragma("unroll") for (int m = 0; m < 4; ++m) _Pragma("unroll") for (int n = 0; n < 2; ++n) _Pragma("unroll") for (int k = 0; k < 2; ++k) \
;         acc[ai][bj][m][n] = __builtin_amdgcn_mfma_f32_16x16x32_bf16(Bt[n][k], At[m][k], acc[ai][bj][m][n], 0, 0, 0); __builtin_amdgcn_s_setprio(0); } while (0)
; #define PG8_WAIT_L(n) asm volatile("s_waitcnt lgkmcnt(" #n ")" ::: "memory")
; #define PG8_BAR __builtin_amdgcn_s_barrier()
; #define PG8_SCHED __builtin_amdgcn_sched_barrier(0)
; __device__ __forceinline__ void gemm_phase(LAS unsigned char* lds, const GemmD& g) {
;     ...
;         for (int t = 0; t < nt; t += 2) {
;             const bool last = (t == nt - 2);
;             const char* a1 = cA + (size_t)(t + 1) * kstep;
;             const char* a2 = last ? nA : cA + (size_t)(t + 2) * kstep; const char* b2 = last ? nB : cB + (size_t)(t + 2) * kstep;
;             const char* a3 = a2 + kstep; const char* b3 = b2 + kstep;
;             PG8_LDB(B0, 0, 0); PG8_SCHED; PG8_LDA(At, 0, 0); PG8_STAGE(PG8_SA(1, 1), a1 + hstep, voffA);
;             PG8_WAIT_L(8); PG8_BAR; PG8_WAIT_L(0); PG8_MMA(0, 0, At, B0); PG8_BAR; PG8_SCHED;
.LBB0_145:
	s_add_i32 s6, 0, 0x10000
	s_add_i32 m0, s2, 0xc000
	s_nop 0
	global_load_lds_dwordx4 v174, s[98:99]
	s_add_i32 m0, s2, 0xe000
	s_nop 0
	global_load_lds_dwordx4 v176, s[98:99]
	ds_read_b128 v[136:139], v244
	ds_read_b128 v[140:143], v244 offset:1024
	ds_read_b128 v[144:147], v244 offset:2048
	ds_read_b128 v[148:151], v244 offset:3072
	v_cmp_eq_u32_e32 vcc, s4, v135
	s_add_i32 s5, s4, 2
	ds_read_b128 v[152:155], v233
	ds_read_b128 v[156:159], v233 offset:1024
	ds_read_b128 v[160:163], v233 offset:2048
	ds_read_b128 v[184:187], v233 offset:3072
	ds_read_b128 v[188:191], v233 offset:4096
	ds_read_b128 v[192:195], v233 offset:5120
	ds_read_b128 v[196:199], v233 offset:6144
	ds_read_b128 v[200:203], v233 offset:7168
	s_waitcnt lgkmcnt(8)
	s_barrier
	s_waitcnt lgkmcnt(0)
	v_mfma_f32_16x16x32_bf16 v[126:129], v[136:139], v[152:155], v[126:129]
	v_mfma_f32_16x16x32_bf16 v[122:125], v[144:147], v[152:155], v[122:125]
	v_mfma_f32_16x16x32_bf16 v[110:113], v[136:139], v[160:163], v[110:113]
	v_mfma_f32_16x16x32_bf16 v[106:109], v[144:147], v[160:163], v[106:109]
	v_mfma_f32_16x16x32_bf16 v[94:97], v[136:139], v[188:191], v[94:97]
	v_mfma_f32_16x16x32_bf16 v[90:93], v[144:147], v[188:191], v[90:93]
	v_mfma_f32_16x16x32_bf16 v[78:81], v[136:139], v[196:199], v[78:81]
	v_mfma_f32_16x16x32_bf16 v[74:77], v[144:147], v[196:199], v[74:77]
	v_mfma_f32_16x16x32_bf16 v[126:129], v[140:143], v[156:159], v[126:129]
	v_mfma_f32_16x16x32_bf16 v[122:125], v[148:151], v[156:159], v[122:125]
	v_mfma_f32_16x16x32_bf16 v[110:113], v[140:143], v[184:187], v[110:113]
	v_mfma_f32_16x16x32_bf16 v[106:109], v[148:151], v[184:187], v[106:109]
	v_mfma_f32_16x16x32_bf16 v[94:97], v[140:143], v[192:195], v[94:97]
	v_mfma_f32_16x16x32_bf16 v[90:93], v[148:151], v[192:195], v[90:93]
	v_mfma_f32_16x16x32_bf16 v[78:81], v[140:143], v[200:203], v[78:81]
	v_mfma_f32_16x16x32_bf16 v[74:77], v[148:151], v[200:203], v[74:77]
	s_barrier
	s_cbranch_vccz .Lkl_notlast
	v_readfirstlane_b32 s98, v180
	v_readfirstlane_b32 s99, v181
	v_readfirstlane_b32 s100, v182
	v_readfirstlane_b32 s101, v183
	s_branch .Lkl_ptr_done

; #define PG8_STAGE(bufoff, gbase, voff) do { _Pragma("unroll") for (int _i = 0; _i < 2; ++_i) \
;         __builtin_amdgcn_global_load_lds((const unsigned*)((const char*)(gbase) + (voff)[_i]), (LAS unsigned*)(lds + (bufoff) + ldsw + _i * 8192), 16, 0, 0); } while (0)
; #define PG8_LDA(dst, b, h) do { _Pragma("unroll") for (int m = 0; m < 4; ++m) _Pragma("unroll") for (int k = 0; k < 2; ++k) dst[m][k] = *(const LAS bf16x8*)(lds + PG8_SA(b, h) + aoff + m * 2048 + k * 1024); } while (0)
; #define PG8_LDB(dst, b, h) do { _Pragma("unroll") for (int n = 0; n < 2; ++n) _Pragma("unroll") for (int k = 0; k < 2; ++k) dst[n][k] = *(const LAS bf16x8*)(lds + PG8_SB(b, h) + boff + n * 2048 + k * 1024); } while (0)
; #define PG8_MMA(ai, bj, At, Bt) do { __builtin_amdgcn_s_setprio(1); _Pragma("unroll") for (int m = 0; m < 4; ++m) _Pragma("unroll") for (int n = 0; n < 2; ++n) _Pragma("unroll") for (int k = 0; k < 2; ++k) \
;         acc[ai][bj][m][n] = __builtin_amdgcn_mfma_f32_16x16x32_bf16(Bt[n][k], At[m][k], acc[ai][bj][m][n], 0, 0, 0); __builtin_amdgcn_s_setprio(0); } while (0)
; #define PG8_WAIT_V(n) asm volatile("s_waitcnt vmcnt(" #n ")" ::: "memory")
; #define PG8_WAIT_L(n) asm volatile("s_waitcnt lgkmcnt(" #n ")" ::: "memory")
; #define PG8_BAR __builtin_amdgcn_s_barrier()
; #define PG8_SCHED __builtin_amdgcn_sched_barrier(0)
; __device__ __forceinline__ void gemm_phase(LAS unsigned char* lds, const GemmD& g) {
;     ...
;             PG8_LDB(B1, 0, 1); PG8_STAGE(PG8_SB(0, 0), b2, voffB);
;             PG8_BAR; PG8_WAIT_L(0); PG8_MMA(0, 1, At, B1); PG8_BAR;
;             PG8_LDA(At, 0, 1); PG8_STAGE(PG8_SA(0, 0), a2, voffA);
;             PG8_BAR; PG8_WAIT_L(0); PG8_MMA(1, 0, At, B0); PG8_BAR; PG8_SCHED;
;             PG8_STAGE(PG8_SB(0, 1), b2 + hstep, voffB);
;             PG8_WAIT_V(6); PG8_BAR; PG8_MMA(1, 1, At, B1); PG8_BAR;
;             PG8_LDB(B0, 1, 0); PG8_SCHED; PG8_LDA(At, 1, 0); PG8_STAGE(PG8_SA(0, 1), a2 + hstep, voffA);
;             PG8_WAIT_L(8); PG8_BAR; PG8_WAIT_L(0); PG8_MMA(0, 0, At, B0); PG8_BAR; PG8_SCHED;
.Lkl_ptr_done:
	s_add_i32 s4, 0, 0x14000
	s_add_i32 s6, s6, s87
	s_mov_b32 m0, s6
	ds_read_b128 v[204:207], v245
	ds_read_b128 v[208:211], v245 offset:1024
	ds_read_b128 v[234:237], v245 offset:2048
	ds_read_b128 v[238:241], v245 offset:3072
	global_load_lds_dwordx4 v172, s[100:101]
	s_add_i32 m0, s6, 0x2000
	s_nop 0
	global_load_lds_dwordx4 v168, s[100:101]
	s_barrier
	s_waitcnt lgkmcnt(0)
	v_mfma_f32_16x16x32_bf16 v[118:121], v[204:207], v[152:155], v[118:121]
	v_mfma_f32_16x16x32_bf16 v[114:117], v[234:237], v[152:155], v[114:117]
	v_mfma_f32_16x16x32_bf16 v[102:105], v[204:207], v[160:163], v[102:105]
	v_mfma_f32_16x16x32_bf16 v[98:101], v[234:237], v[160:163], v[98:101]
	v_mfma_f32_16x16x32_bf16 v[86:89], v[204:207], v[188:191], v[86:89]
	v_mfma_f32_16x16x32_bf16 v[82:85], v[234:237], v[188:191], v[82:85]
	v_mfma_f32_16x16x32_bf16 v[70:73], v[204:207], v[196:199], v[70:73]
	v_mfma_f32_16x16x32_bf16 v[66:69], v[234:237], v[196:199], v[66:69]
	v_mfma_f32_16x16x32_bf16 v[118:121], v[208:211], v[156:159], v[118:121]
	v_mfma_f32_16x16x32_bf16 v[114:117], v[238:241], v[156:159], v[114:117]
	v_mfma_f32_16x16x32_bf16 v[102:105], v[208:211], v[184:187], v[102:105]
	v_mfma_f32_16x16x32_bf16 v[98:101], v[238:241], v[184:187], v[98:101]
	v_mfma_f32_16x16x32_bf16 v[86:89], v[208:211], v[192:195], v[86:89]
	v_mfma_f32_16x16x32_bf16 v[82:85], v[238:241], v[192:195], v[82:85]
	v_mfma_f32_16x16x32_bf16 v[70:73], v[208:211], v[200:203], v[70:73]
	v_mfma_f32_16x16x32_bf16 v[66:69], v[238:241], v[200:203], v[66:69]
	s_barrier
	s_mov_b32 m0, s2
	ds_read_b128 v[152:155], v233 offset:16384
	ds_read_b128 v[156:159], v233 offset:17408
	ds_read_b128 v[160:163], v233 offset:18432
	ds_read_b128 v[184:187], v233 offset:19456
	ds_read_b128 v[188:191], v233 offset:20480
	ds_read_b128 v[192:195], v233 offset:21504
	ds_read_b128 v[196:199], v233 offset:22528
	ds_read_b128 v[200:203], v233 offset:23552
	global_load_lds_dwordx4 v170, s[98:99]
	s_mov_b32 m0, s3
	s_nop 0
	global_load_lds_dwordx4 v166, s[98:99]
	s_barrier
	s_waitcnt lgkmcnt(0)
	v_mfma_f32_16x16x32_bf16 v[62:65], v[136:139], v[152:155], v[62:65]
	v_mfma_f32_16x16x32_bf16 v[58:61], v[144:147], v[152:155], v[58:61]
	v_mfma_f32_16x16x32_bf16 v[46:49], v[136:139], v[160:163], v[46:49]
	v_mfma_f32_16x16x32_bf16 v[42:45], v[144:147], v[160:163], v[42:45]
	v_mfma_f32_16x16x32_bf16 v[30:33], v[136:139], v[188:191], v[30:33]
	v_mfma_f32_16x16x32_bf16 v[26:29], v[144:147], v[188:191], v[26:29]
	v_mfma_f32_16x16x32_bf16 v[14:17], v[136:139], v[196:199], v[14:17]
	v_mfma_f32_16x16x32_bf16 v[10:13], v[144:147], v[196:199], v[10:13]
	v_mfma_f32_16x16x32_bf16 v[62:65], v[140:143], v[156:159], v[62:65]
	v_mfma_f32_16x16x32_bf16 v[58:61], v[148:151], v[156:159], v[58:61]
	v_mfma_f32_16x16x32_bf16 v[46:49], v[140:143], v[184:187], v[46:49]
	v_mfma_f32_16x16x32_bf16 v[42:45], v[148:151], v[184:187], v[42:45]
	v_mfma_f32_16x16x32_bf16 v[30:33], v[140:143], v[192:195], v[30:33]
	v_mfma_f32_16x16x32_bf16 v[26:29], v[148:151], v[192:195], v[26:29]
	v_mfma_f32_16x16x32_bf16 v[14:17], v[140:143], v[200:203], v[14:17]
	v_mfma_f32_16x16x32_bf16 v[10:13], v[148:151], v[200:203], v[10:13]
	s_barrier
	s_add_i32 s4, s4, s87
	s_mov_b32 m0, s4
	s_nop 0
	global_load_lds_dwordx4 v242, s[100:101]
	s_add_i32 m0, s4, 0x2000
	s_nop 0
	global_load_lds_dwordx4 v243, s[100:101]
	s_waitcnt vmcnt(6)
	s_barrier
	v_mfma_f32_16x16x32_bf16 v[54:57], v[204:207], v[152:155], v[54:57]
	v_mfma_f32_16x16x32_bf16 v[50:53], v[234:237], v[152:155], v[50:53]
	v_mfma_f32_16x16x32_bf16 v[38:41], v[204:207], v[160:163], v[38:41]
	v_mfma_f32_16x16x32_bf16 v[34:37], v[234:237], v[160:163], v[34:37]
	v_mfma_f32_16x16x32_bf16 v[22:25], v[204:207], v[188:191], v[22:25]
	v_mfma_f32_16x16x32_bf16 v[18:21], v[234:237], v[188:191], v[18:21]
	v_mfma_f32_16x16x32_bf16 v[6:9], v[204:207], v[196:199], v[6:9]
	v_mfma_f32_16x16x32_bf16 v[2:5], v[234:237], v[196:199], v[2:5]
	v_mfma_f32_16x16x32_bf16 v[54:57], v[208:211], v[156:159], v[54:57]
	v_mfma_f32_16x16x32_bf16 v[50:53], v[238:241], v[156:159], v[50:53]
	v_mfma_f32_16x16x32_bf16 v[38:41], v[208:211], v[184:187], v[38:41]
	v_mfma_f32_16x16x32_bf16 v[34:37], v[238:241], v[184:187], v[34:37]
	v_mfma_f32_16x16x32_bf16 v[22:25], v[208:211], v[192:195], v[22:25]
	v_mfma_f32_16x16x32_bf16 v[18:21], v[238:241], v[192:195], v[18:21]
	v_mfma_f32_16x16x32_bf16 v[6:9], v[208:211], v[200:203], v[6:9]
	v_mfma_f32_16x16x32_bf16 v[2:5], v[238:241], v[200:203], v[2:5]
	s_barrier
	s_add_i32 s4, 0, 0x18000
	s_mov_b32 m0, s64
	s_nop 0
	global_load_lds_dwordx4 v174, s[98:99]
	s_mov_b32 m0, s65
	s_nop 0
	global_load_lds_dwordx4 v176, s[98:99]
	ds_read_b128 v[136:139], v246
	ds_read_b128 v[140:143], v246 offset:1024
	ds_read_b128 v[144:147], v246 offset:2048
	ds_read_b128 v[148:151], v246 offset:3072
	ds_read_b128 v[152:155], v233 offset:32768
	ds_read_b128 v[156:159], v233 offset:33792
	ds_read_b128 v[160:163], v233 offset:34816
	ds_read_b128 v[184:187], v233 offset:35840
	ds_read_b128 v[188:191], v233 offset:36864
	ds_read_b128 v[192:195], v233 offset:37888
	ds_read_b128 v[196:199], v233 offset:38912
	ds_read_b128 v[200:203], v233 offset:39936
	s_waitcnt lgkmcnt(8)
	s_barrier
; #define PG8_STAGE(bufoff, gbase, voff) do { _Pragma("unroll") for (int _i = 0; _i < 2; ++_i) \
;         __builtin_amdgcn_global_load_lds((const unsigned*)((const char*)(gbase) + (voff)[_i]), (LAS unsigned*)(lds + (bufoff) + ldsw + _i * 8192), 16, 0, 0); } while (0)
; #define PG8_LDA(dst, b, h) do { _Pragma("unroll") for (int m = 0; m < 4; ++m) _Pragma("unroll") for (int k = 0; k < 2; ++k) dst[m][k] = *(const LAS bf16x8*)(lds + PG8_SA(b, h) + aoff + m * 2048 + k * 1024); } while (0)
; #define PG8_LDB(dst, b, h) do { _Pragma("unroll") for (int n = 0; n < 2; ++n) _Pragma("unroll") for (int k = 0; k < 2; ++k) dst[n][k] = *(const LAS bf16x8*)(lds + PG8_SB(b, h) + boff + n * 2048 + k * 1024); } while (0)
; #define PG8_MMA(ai, bj, At, Bt) do { __builtin_amdgcn_s_setprio(1); _Pragma("unroll") for (int m = 0; m < 4; ++m) _Pragma("unroll") for (int n = 0; n < 2; ++n) _Pragma("unroll") for (int k = 0; k < 2; ++k) \
;         acc[ai][bj][m][n] = __builtin_amdgcn_mfma_f32_16x16x32_bf16(Bt[n][k], At[m][k], acc[ai][bj][m][n], 0, 0, 0); __builtin_amdgcn_s_setprio(0); } while (0)
; #define PG8_WAIT_V(n) asm volatile("s_waitcnt vmcnt(" #n ")" ::: "memory")
; #define PG8_WAIT_L(n) asm volatile("s_waitcnt lgkmcnt(" #n ")" ::: "memory")
; #define PG8_BAR __builtin_amdgcn_s_barrier()
; #define PG8_SCHED __builtin_amdgcn_sched_barrier(0)
; __device__ __forceinline__ void gemm_epilogue(const GemmD& g, const f32x4 (&acc)[2][2][4][2], const Unit& u, int wr, int wc, int fr, int fq) {
;     const int row0 = u.pm * BM + wr * 64 + fr;
;     const int mode = g.mode;
;     if (u.part >= 0) {
; __device__ __forceinline__ void gemm_phase(LAS unsigned char* lds, const GemmD& g) {
;     ...
;             PG8_WAIT_L(8); PG8_BAR; PG8_WAIT_L(0); PG8_MMA(0, 0, At, B0); PG8_BAR; PG8_SCHED;
;             PG8_LDB(B1, 1, 1); PG8_STAGE(PG8_SB(1, 0), b3, voffB);
;             PG8_BAR; PG8_WAIT_L(0); PG8_MMA(0, 1, At, B1); PG8_BAR;
;             PG8_LDA(At, 1, 1); PG8_STAGE(PG8_SA(1, 0), a3, voffA);
;             PG8_BAR; PG8_WAIT_L(0); PG8_MMA(1, 0, At, B0); PG8_BAR; PG8_SCHED;
;             PG8_STAGE(PG8_SB(1, 1), b3 + hstep, voffB);
;             PG8_WAIT_V(6); PG8_BAR; PG8_MMA(1, 1, At, B1); PG8_BAR;
;         }
	s_waitcnt lgkmcnt(0)
	v_mfma_f32_16x16x32_bf16 v[126:129], v[136:139], v[152:155], v[126:129]
	v_mfma_f32_16x16x32_bf16 v[122:125], v[144:147], v[152:155], v[122:125]
	v_mfma_f32_16x16x32_bf16 v[110:113], v[136:139], v[160:163], v[110:113]
	v_mfma_f32_16x16x32_bf16 v[106:109], v[144:147], v[160:163], v[106:109]
	v_mfma_f32_16x16x32_bf16 v[94:97], v[136:139], v[188:191], v[94:97]
	v_mfma_f32_16x16x32_bf16 v[90:93], v[144:147], v[188:191], v[90:93]
	v_mfma_f32_16x16x32_bf16 v[78:81], v[136:139], v[196:199], v[78:81]
	v_mfma_f32_16x16x32_bf16 v[74:77], v[144:147], v[196:199], v[74:77]
	v_mfma_f32_16x16x32_bf16 v[126:129], v[140:143], v[156:159], v[126:129]
	v_mfma_f32_16x16x32_bf16 v[122:125], v[148:151], v[156:159], v[122:125]
	v_mfma_f32_16x16x32_bf16 v[110:113], v[140:143], v[184:187], v[110:113]
	v_mfma_f32_16x16x32_bf16 v[106:109], v[148:151], v[184:187], v[106:109]
	v_mfma_f32_16x16x32_bf16 v[94:97], v[140:143], v[192:195], v[94:97]
	v_mfma_f32_16x16x32_bf16 v[90:93], v[148:151], v[192:195], v[90:93]
	v_mfma_f32_16x16x32_bf16 v[78:81], v[140:143], v[200:203], v[78:81]
	v_mfma_f32_16x16x32_bf16 v[74:77], v[148:151], v[200:203], v[74:77]
	s_barrier
	s_add_i32 s6, 0, 0x1c000
	s_add_i32 s4, s4, s87
	ds_read_b128 v[204:207], v247
	ds_read_b128 v[208:211], v247 offset:1024
	ds_read_b128 v[234:237], v247 offset:2048
	ds_read_b128 v[238:241], v247 offset:3072
	s_add_u32 s100, s100, 0x80
	s_addc_u32 s101, s101, 0
	s_mov_b32 m0, s4
	s_nop 0
	global_load_lds_dwordx4 v172, s[100:101]
	s_add_i32 m0, s4, 0x2000
	s_nop 0
	global_load_lds_dwordx4 v168, s[100:101]
	s_barrier
	s_waitcnt lgkmcnt(0)
	v_mfma_f32_16x16x32_bf16 v[118:121], v[204:207], v[152:155], v[118:121]
	v_mfma_f32_16x16x32_bf16 v[114:117], v[234:237], v[152:155], v[114:117]
	v_mfma_f32_16x16x32_bf16 v[102:105], v[204:207], v[160:163], v[102:105]
	v_mfma_f32_16x16x32_bf16 v[98:101], v[234:237], v[160:163], v[98:101]
	v_mfma_f32_16x16x32_bf16 v[86:89], v[204:207], v[188:191], v[86:89]
	v_mfma_f32_16x16x32_bf16 v[82:85], v[234:237], v[188:191], v[82:85]
	v_mfma_f32_16x16x32_bf16 v[70:73], v[204:207], v[196:199], v[70:73]
	v_mfma_f32_16x16x32_bf16 v[66:69], v[234:237], v[196:199], v[66:69]
	v_mfma_f32_16x16x32_bf16 v[118:121], v[208:211], v[156:159], v[118:121]
	v_mfma_f32_16x16x32_bf16 v[114:117], v[238:241], v[156:159], v[114:117]
	v_mfma_f32_16x16x32_bf16 v[102:105], v[208:211], v[184:187], v[102:105]
	v_mfma_f32_16x16x32_bf16 v[98:101], v[238:241], v[184:187], v[98:101]
	v_mfma_f32_16x16x32_bf16 v[86:89], v[208:211], v[192:195], v[86:89]
	v_mfma_f32_16x16x32_bf16 v[82:85], v[238:241], v[192:195], v[82:85]
	v_mfma_f32_16x16x32_bf16 v[70:73], v[208:211], v[200:203], v[70:73]
	v_mfma_f32_16x16x32_bf16 v[66:69], v[238:241], v[200:203], v[66:69]
	s_barrier
	s_mov_b32 m0, s28
	s_add_u32 s98, s98, 0x80
	s_addc_u32 s99, s99, 0
	ds_read_b128 v[152:155], v233 offset:49152
	ds_read_b128 v[156:159], v233 offset:50176
	ds_read_b128 v[160:163], v233 offset:51200
	ds_read_b128 v[184:187], v233 offset:52224
	ds_read_b128 v[188:191], v233 offset:53248
	ds_read_b128 v[192:195], v233 offset:54272
	ds_read_b128 v[196:199], v233 offset:55296
	ds_read_b128 v[200:203], v233 offset:56320
	global_load_lds_dwordx4 v170, s[98:99]
	s_mov_b32 m0, s29
	s_nop 0
	global_load_lds_dwordx4 v166, s[98:99]
	s_barrier
	s_waitcnt lgkmcnt(0)
	v_mfma_f32_16x16x32_bf16 v[62:65], v[136:139], v[152:155], v[62:65]
	v_mfma_f32_16x16x32_bf16 v[58:61], v[144:147], v[152:155], v[58:61]
	v_mfma_f32_16x16x32_bf16 v[46:49], v[136:139], v[160:163], v[46:49]
	v_mfma_f32_16x16x32_bf16 v[42:45], v[144:147], v[160:163], v[42:45]
	v_mfma_f32_16x16x32_bf16 v[30:33], v[136:139], v[188:191], v[30:33]
	v_mfma_f32_16x16x32_bf16 v[26:29], v[144:147], v[188:191], v[26:29]
	v_mfma_f32_16x16x32_bf16 v[14:17], v[136:139], v[196:199], v[14:17]
	v_mfma_f32_16x16x32_bf16 v[10:13], v[144:147], v[196:199], v[10:13]
	v_mfma_f32_16x16x32_bf16 v[62:65], v[140:143], v[156:159], v[62:65]
	v_mfma_f32_16x16x32_bf16 v[58:61], v[148:151], v[156:159], v[58:61]
	v_mfma_f32_16x16x32_bf16 v[46:49], v[140:143], v[184:187], v[46:49]
	v_mfma_f32_16x16x32_bf16 v[42:45], v[148:151], v[184:187], v[42:45]
	v_mfma_f32_16x16x32_bf16 v[30:33], v[140:143], v[192:195], v[30:33]
	v_mfma_f32_16x16x32_bf16 v[26:29], v[148:151], v[192:195], v[26:29]
	v_mfma_f32_16x16x32_bf16 v[14:17], v[140:143], v[200:203], v[14:17]
	v_mfma_f32_16x16x32_bf16 v[10:13], v[148:151], v[200:203], v[10:13]
	s_barrier
	s_add_i32 s4, s6, s87
	s_mov_b32 m0, s4
	s_nop 0
	global_load_lds_dwordx4 v242, s[100:101]
	s_add_i32 m0, s4, 0x2000
	s_nop 0
	global_load_lds_dwordx4 v243, s[100:101]
	s_add_u32 s100, s100, 0x80
	s_addc_u32 s101, s101, 0
	s_mov_b32 s4, s5
	s_waitcnt vmcnt(6)
	s_barrier
	v_mfma_f32_16x16x32_bf16 v[54:57], v[204:207], v[152:155], v[54:57]
	v_mfma_f32_16x16x32_bf16 v[50:53], v[234:237], v[152:155], v[50:53]
	v_mfma_f32_16x16x32_bf16 v[38:41], v[204:207], v[160:163], v[38:41]
	v_mfma_f32_16x16x32_bf16 v[34:37], v[234:237], v[160:163], v[34:37]
	v_mfma_f32_16x16x32_bf16 v[22:25], v[204:207], v[188:191], v[22:25]
	v_mfma_f32_16x16x32_bf16 v[18:21], v[234:237], v[188:191], v[18:21]
	v_mfma_f32_16x16x32_bf16 v[6:9], v[204:207], v[196:199], v[6:9]
	v_mfma_f32_16x16x32_bf16 v[2:5], v[234:237], v[196:199], v[2:5]
	v_mfma_f32_16x16x32_bf16 v[54:57], v[208:211], v[156:159], v[54:57]
	v_mfma_f32_16x16x32_bf16 v[50:53], v[238:241], v[156:159], v[50:53]
	v_mfma_f32_16x16x32_bf16 v[38:41], v[208:211], v[184:187], v[38:41]
	v_mfma_f32_16x16x32_bf16 v[34:37], v[238:241], v[184:187], v[34:37]
	v_mfma_f32_16x16x32_bf16 v[22:25], v[208:211], v[192:195], v[22:25]
	v_mfma_f32_16x16x32_bf16 v[18:21], v[238:241], v[192:195], v[18:21]
	v_mfma_f32_16x16x32_bf16 v[6:9], v[208:211], v[200:203], v[6:9]
	v_mfma_f32_16x16x32_bf16 v[2:5], v[238:241], v[200:203], v[2:5]
	s_barrier
	s_cbranch_vccz .LBB0_145
	v_lshl_add_u32 v184, s56, 8, v228
	s_cmp_lt_i32 s66, 0
	s_mov_b64 s[4:5], -1
	s_cbranch_scc0 .LBB0_704
